# lean hand-written EpiProj epilogue in GEMM1 (saddr stores, no per-store branching)
# speedup vs baseline: 1.0016x; 1.0016x over previous
; __device__ __forceinline__ unsigned cvtpk(float lo, float hi) { f32x2_t v = {lo, hi}; f16x2_t b = __builtin_convertvector(v, f16x2_t); return __builtin_bit_cast(unsigned, b); }
;     __device__ __forceinline__ void operator()(const f32x4 (&acc)[2][2][4][2], const Unit& u, int wr, int wc, int fr, int fq) const {
;         const int row0 = u.pm * BM + wr * 64 + fr; const int pn = u.pn;
;         float rs[2][4];
; #pragma unroll
;         for (int ai = 0; ai < 2; ++ai)
; #pragma unroll
;             for (int m = 0; m < 4; ++m) rs[ai][m] = rsl[ai * HALF + wr * 64 + m * 16 + fr];
; #pragma unroll
;         for (int ai = 0; ai < 2; ++ai)
; #pragma unroll
;             for (int m = 0; m < 4; ++m) { const int row = row0 + ai * HALF + m * 16; const int bl = row >> 12, t = row & 4095;
; #pragma unroll
;                 for (int bj = 0; bj < 2; ++bj) { const f32x4 v0 = acc[ai][bj][m][0] * rs[ai][m], v1 = acc[ai][bj][m][1] * rs[ai][m];
;                     u32x4 w; w.x = cvtpk(v0[0], v0[1]); w.y = cvtpk(v0[2], v0[3]); w.z = cvtpk(v1[0], v1[1]); w.w = cvtpk(v1[2], v1[3]);
;                     const int ct = bj * HALF + wc * 32 + 8 * fq;
;                     bf16_t* dst;
;                     if (pn < 18) { const int sect = pn / 6, hh = (pn - sect * 6) * 4 + (ct >> 6), dsh = 2 * (hh >> 3); const int idx = ((t & ((1 << dsh) - 1)) << (12 - dsh)) + (t >> dsh);
;                         dst = P + PL_A + ((size_t)((bl * 3 + sect) * 24 + hh) * 4096 + idx) * 64 + (ct & 63); }
;                     else if (pn < 22) { const int qk = (pn - 18) >> 1, head = ((pn - 18) & 1) * 2 + (ct >> 7);
;                         dst = P + PL_QR + (size_t)qk * PL_QK_SZ + ((size_t)(bl * 4 + head) * 4096 + t) * 128 + (ct & 127); }
;                     else if (pn < 30) { const int vg = (pn - 22) >> 2, head = (pn - 22) & 3;
;                         dst = P + PL_VR + (size_t)vg * PL_VG_SZ + ((size_t)(bl * 4 + head) * 4096 + t) * 256 + ct; }
;                     else dst = G + (size_t)row * 2048 + (pn - 30) * 256 + ct;
;                     *(u32x4*)dst = w; } }
.LBB0_156:
	ds_read2_b32 v[150:151], v181 offset1:16
	ds_read2_b32 v[148:149], v181 offset0:32 offset1:48
	ds_read2_b32 v[146:147], v181 offset0:128 offset1:144
	ds_read2_b32 v[142:143], v181 offset0:160 offset1:176
	s_lshl_b32 s1, s24, 8
	s_add_i32 s1, s1, s82
	s_lshr_b32 s25, s1, 12
	s_and_b32 s26, s1, 0xfff
	v_lshlrev_b32_e32 v183, 1, v161
	s_cmp_gt_i32 s40, 17
	s_cbranch_scc1 .Lepi1_notA
	s_mul_hi_u32 s27, s40, 0x2aaaaaab
	s_mul_i32 s28, s27, 6
	s_sub_i32 s28, s40, s28
	s_and_b32 s29, s28, -2
	s_mul_i32 s32, s25, 3
	s_add_i32 s32, s32, s27
	s_mul_i32 s32, s32, 24
	s_lshl_b32 s28, s28, 2
	s_add_i32 s32, s32, s28
	s_add_i32 s32, s32, s14
	s_lshr_b32 s26, s26, s29
	s_lshl_b32 s26, s26, 7
	s_lshr_b32 s41, s32, 13
	s_lshl_b32 s32, s32, 19
	s_add_u32 s100, s74, s32
	s_addc_u32 s101, s75, s41
	s_add_u32 s100, s100, s26
	s_addc_u32 s101, s101, 0
	s_lshl_b32 s27, 1, s29
	s_add_i32 s27, s27, -1
	s_sub_i32 s28, 12, s29
	v_and_b32_e32 v184, s27, v159
	v_lshlrev_b32_e32 v184, s28, v184
	v_lshrrev_b32_e32 v185, s29, v159
	v_add_lshl_u32 v184, v184, v185, 7
	v_and_b32_e32 v183, 63, v161
	v_lshl_add_u32 v183, v183, 1, v184
	s_lshr_b32 s45, 0x800, s29
	s_lshr_b32 s55, 0x4000, s29
	s_mov_b32 s57, 0x100000
	s_branch .Lepi1_go
.Lepi1_notA:
	s_cmp_gt_i32 s40, 21
	s_cbranch_scc1 .Lepi1_notB
	s_sub_i32 s27, s40, 18
	s_lshr_b32 s28, s27, 1
	s_and_b32 s27, s27, 1
	s_lshl_b32 s27, s27, 1
	s_lshl_b32 s29, s25, 2
	s_add_i32 s29, s29, s27
	s_lshl_b32 s29, s29, 12
	s_add_i32 s29, s29, s26
	s_lshl_b32 s29, s29, 8
	s_lshl_b32 s28, s28, 24
	s_add_i32 s29, s29, s28
	s_add_i32 s29, s29, 0x9000000
	s_add_u32 s100, s74, s29
	s_addc_u32 s101, s75, 0
	v_lshl_add_u32 v183, v159, 8, v183
	s_movk_i32 s45, 0x1000
	s_mov_b32 s55, 0x8000
	s_mov_b32 s57, 0x100000
	s_branch .Lepi1_go
.Lepi1_notB:
	s_cmp_gt_i32 s40, 29
	s_cbranch_scc1 .Lepi1_caseD
	s_sub_i32 s27, s40, 22
	s_lshr_b32 s28, s27, 2
	s_and_b32 s27, s27, 3
	s_lshl_b32 s29, s25, 2
	s_add_i32 s29, s29, s27
	s_lshl_b32 s29, s29, 12
	s_add_i32 s29, s29, s26
	s_lshl_b32 s29, s29, 9
	s_lshl_b32 s28, s28, 25
	s_add_i32 s29, s29, s28
	s_add_i32 s29, s29, 0xb000000
	s_add_u32 s100, s74, s29
	s_addc_u32 s101, s75, 0
	v_lshl_add_u32 v183, v159, 9, v183
	s_movk_i32 s45, 0x2000
	s_mov_b32 s55, 0x10000
	s_movk_i32 s57, 0x100
	s_branch .Lepi1_go
.Lepi1_caseD:
	s_lshl_b32 s27, s1, 12
	s_sub_i32 s28, s40, 30
	s_lshl_b32 s28, s28, 9
	s_add_i32 s27, s27, s28
	s_add_u32 s100, s66, s27
	s_addc_u32 s101, s67, 0
	v_lshl_add_u32 v183, v159, 12, v183
	s_mov_b32 s45, 0x10000
	s_mov_b32 s55, 0x80000
	s_movk_i32 s57, 0x100
.Lepi1_go:
	s_add_i32 s27, s55, s57
	s_waitcnt lgkmcnt(0)
	v_pk_mul_f32 v[126:127], v[126:127], v[150:151] op_sel_hi:[1,0]
	v_pk_mul_f32 v[128:129], v[128:129], v[150:151] op_sel_hi:[1,0]
	v_pk_mul_f32 v[122:123], v[122:123], v[150:151] op_sel_hi:[1,0]
	v_pk_mul_f32 v[124:125], v[124:125], v[150:151] op_sel_hi:[1,0]
	v_cvt_pk_f16_f32 v126, v126, v127
	v_cvt_pk_f16_f32 v127, v128, v129
	v_cvt_pk_f16_f32 v128, v122, v123
	v_cvt_pk_f16_f32 v129, v124, v125
	v_mov_b32_e32 v184, v183
	global_store_dwordx4 v184, v[126:129], s[100:101]
	v_pk_mul_f32 v[110:111], v[110:111], v[150:151] op_sel:[0,1] op_sel_hi:[1,1]
	v_pk_mul_f32 v[112:113], v[112:113], v[150:151] op_sel:[0,1] op_sel_hi:[1,1]
	v_pk_mul_f32 v[106:107], v[106:107], v[150:151] op_sel:[0,1] op_sel_hi:[1,1]
	v_pk_mul_f32 v[108:109], v[108:109], v[150:151] op_sel:[0,1] op_sel_hi:[1,1]
	v_cvt_pk_f16_f32 v110, v110, v111
	v_cvt_pk_f16_f32 v111, v112, v113
	v_cvt_pk_f16_f32 v112, v106, v107
	v_cvt_pk_f16_f32 v113, v108, v109
	v_add_u32_e32 v185, s45, v184
	global_store_dwordx4 v185, v[110:113], s[100:101]
	v_pk_mul_f32 v[94:95], v[94:95], v[148:149] op_sel_hi:[1,0]
	v_pk_mul_f32 v[96:97], v[96:97], v[148:149] op_sel_hi:[1,0]
	v_pk_mul_f32 v[90:91], v[90:91], v[148:149] op_sel_hi:[1,0]
	v_pk_mul_f32 v[92:93], v[92:93], v[148:149] op_sel_hi:[1,0]
	v_cvt_pk_f16_f32 v94, v94, v95
	v_cvt_pk_f16_f32 v95, v96, v97
	v_cvt_pk_f16_f32 v96, v90, v91
	v_cvt_pk_f16_f32 v97, v92, v93
	v_add_u32_e32 v186, s45, v185
	global_store_dwordx4 v186, v[94:97], s[100:101]
	v_pk_mul_f32 v[78:79], v[78:79], v[148:149] op_sel:[0,1] op_sel_hi:[1,1]
	v_pk_mul_f32 v[80:81], v[80:81], v[148:149] op_sel:[0,1] op_sel_hi:[1,1]
	v_pk_mul_f32 v[74:75], v[74:75], v[148:149] op_sel:[0,1] op_sel_hi:[1,1]
	v_pk_mul_f32 v[76:77], v[76:77], v[148:149] op_sel:[0,1] op_sel_hi:[1,1]
	v_cvt_pk_f16_f32 v78, v78, v79
	v_cvt_pk_f16_f32 v79, v80, v81
	v_cvt_pk_f16_f32 v80, v74, v75
	v_cvt_pk_f16_f32 v81, v76, v77
	v_add_u32_e32 v187, s45, v186
	global_store_dwordx4 v187, v[78:81], s[100:101]
	v_pk_mul_f32 v[118:119], v[118:119], v[150:151] op_sel_hi:[1,0]
	v_pk_mul_f32 v[120:121], v[120:121], v[150:151] op_sel_hi:[1,0]
	v_pk_mul_f32 v[114:115], v[114:115], v[150:151] op_sel_hi:[1,0]
	v_pk_mul_f32 v[116:117], v[116:117], v[150:151] op_sel_hi:[1,0]
	v_cvt_pk_f16_f32 v118, v118, v119
	v_cvt_pk_f16_f32 v119, v120, v121
	v_cvt_pk_f16_f32 v120, v114, v115
	v_cvt_pk_f16_f32 v121, v116, v117
	v_add_u32_e32 v184, s57, v183
	global_store_dwordx4 v184, v[118:121], s[100:101]
	v_pk_mul_f32 v[102:103], v[102:103], v[150:151] op_sel:[0,1] op_sel_hi:[1,1]
	v_pk_mul_f32 v[104:105], v[104:105], v[150:151] op_sel:[0,1] op_sel_hi:[1,1]
	v_pk_mul_f32 v[98:99], v[98:99], v[150:151] op_sel:[0,1] op_sel_hi:[1,1]
	v_pk_mul_f32 v[100:101], v[100:101], v[150:151] op_sel:[0,1] op_sel_hi:[1,1]
	v_cvt_pk_f16_f32 v102, v102, v103
	v_cvt_pk_f16_f32 v103, v104, v105
; __device__ __forceinline__ unsigned cvtpk(float lo, float hi) { f32x2_t v = {lo, hi}; f16x2_t b = __builtin_convertvector(v, f16x2_t); return __builtin_bit_cast(unsigned, b); }
;     __device__ __forceinline__ void operator()(const f32x4 (&acc)[2][2][4][2], const Unit& u, int wr, int wc, int fr, int fq) const {
;     ...
; #pragma unroll
;         for (int ai = 0; ai < 2; ++ai)
; #pragma unroll
;             for (int m = 0; m < 4; ++m) { const int row = row0 + ai * HALF + m * 16; const int bl = row >> 12, t = row & 4095;
; #pragma unroll
;                 for (int bj = 0; bj < 2; ++bj) { const f32x4 v0 = acc[ai][bj][m][0] * rs[ai][m], v1 = acc[ai][bj][m][1] * rs[ai][m];
;                     u32x4 w; w.x = cvtpk(v0[0], v0[1]); w.y = cvtpk(v0[2], v0[3]); w.z = cvtpk(v1[0], v1[1]); w.w = cvtpk(v1[2], v1[3]);
;                     const int ct = bj * HALF + wc * 32 + 8 * fq;
;                     bf16_t* dst;
;                     if (pn < 18) { const int sect = pn / 6, hh = (pn - sect * 6) * 4 + (ct >> 6), dsh = 2 * (hh >> 3); const int idx = ((t & ((1 << dsh) - 1)) << (12 - dsh)) + (t >> dsh);
;                         dst = P + PL_A + ((size_t)((bl * 3 + sect) * 24 + hh) * 4096 + idx) * 64 + (ct & 63); }
;                     else if (pn < 22) { const int qk = (pn - 18) >> 1, head = ((pn - 18) & 1) * 2 + (ct >> 7);
;                         dst = P + PL_QR + (size_t)qk * PL_QK_SZ + ((size_t)(bl * 4 + head) * 4096 + t) * 128 + (ct & 127); }
;                     else if (pn < 30) { const int vg = (pn - 22) >> 2, head = (pn - 22) & 3;
;                         dst = P + PL_VR + (size_t)vg * PL_VG_SZ + ((size_t)(bl * 4 + head) * 4096 + t) * 256 + ct; }
;                     else dst = G + (size_t)row * 2048 + (pn - 30) * 256 + ct;
;                     *(u32x4*)dst = w; } }
	v_cvt_pk_f16_f32 v104, v98, v99
	v_cvt_pk_f16_f32 v105, v100, v101
	v_add_u32_e32 v185, s45, v184
	global_store_dwordx4 v185, v[102:105], s[100:101]
	v_pk_mul_f32 v[86:87], v[86:87], v[148:149] op_sel_hi:[1,0]
	v_pk_mul_f32 v[88:89], v[88:89], v[148:149] op_sel_hi:[1,0]
	v_pk_mul_f32 v[82:83], v[82:83], v[148:149] op_sel_hi:[1,0]
	v_pk_mul_f32 v[84:85], v[84:85], v[148:149] op_sel_hi:[1,0]
	v_cvt_pk_f16_f32 v86, v86, v87
	v_cvt_pk_f16_f32 v87, v88, v89
	v_cvt_pk_f16_f32 v88, v82, v83
	v_cvt_pk_f16_f32 v89, v84, v85
	v_add_u32_e32 v186, s45, v185
	global_store_dwordx4 v186, v[86:89], s[100:101]
	v_pk_mul_f32 v[70:71], v[70:71], v[148:149] op_sel:[0,1] op_sel_hi:[1,1]
	v_pk_mul_f32 v[72:73], v[72:73], v[148:149] op_sel:[0,1] op_sel_hi:[1,1]
	v_pk_mul_f32 v[66:67], v[66:67], v[148:149] op_sel:[0,1] op_sel_hi:[1,1]
	v_pk_mul_f32 v[68:69], v[68:69], v[148:149] op_sel:[0,1] op_sel_hi:[1,1]
	v_cvt_pk_f16_f32 v70, v70, v71
	v_cvt_pk_f16_f32 v71, v72, v73
	v_cvt_pk_f16_f32 v72, v66, v67
	v_cvt_pk_f16_f32 v73, v68, v69
	v_add_u32_e32 v187, s45, v186
	global_store_dwordx4 v187, v[70:73], s[100:101]
	v_pk_mul_f32 v[62:63], v[62:63], v[146:147] op_sel_hi:[1,0]
	v_pk_mul_f32 v[64:65], v[64:65], v[146:147] op_sel_hi:[1,0]
	v_pk_mul_f32 v[58:59], v[58:59], v[146:147] op_sel_hi:[1,0]
	v_pk_mul_f32 v[60:61], v[60:61], v[146:147] op_sel_hi:[1,0]
	v_cvt_pk_f16_f32 v62, v62, v63
	v_cvt_pk_f16_f32 v63, v64, v65
	v_cvt_pk_f16_f32 v64, v58, v59
	v_cvt_pk_f16_f32 v65, v60, v61
	v_add_u32_e32 v184, s55, v183
	global_store_dwordx4 v184, v[62:65], s[100:101]
	v_pk_mul_f32 v[46:47], v[46:47], v[146:147] op_sel:[0,1] op_sel_hi:[1,1]
	v_pk_mul_f32 v[48:49], v[48:49], v[146:147] op_sel:[0,1] op_sel_hi:[1,1]
	v_pk_mul_f32 v[42:43], v[42:43], v[146:147] op_sel:[0,1] op_sel_hi:[1,1]
	v_pk_mul_f32 v[44:45], v[44:45], v[146:147] op_sel:[0,1] op_sel_hi:[1,1]
	v_cvt_pk_f16_f32 v46, v46, v47
	v_cvt_pk_f16_f32 v47, v48, v49
	v_cvt_pk_f16_f32 v48, v42, v43
	v_cvt_pk_f16_f32 v49, v44, v45
	v_add_u32_e32 v185, s45, v184
	global_store_dwordx4 v185, v[46:49], s[100:101]
	v_pk_mul_f32 v[30:31], v[30:31], v[142:143] op_sel_hi:[1,0]
	v_pk_mul_f32 v[32:33], v[32:33], v[142:143] op_sel_hi:[1,0]
	v_pk_mul_f32 v[26:27], v[26:27], v[142:143] op_sel_hi:[1,0]
	v_pk_mul_f32 v[28:29], v[28:29], v[142:143] op_sel_hi:[1,0]
	v_cvt_pk_f16_f32 v30, v30, v31
	v_cvt_pk_f16_f32 v31, v32, v33
	v_cvt_pk_f16_f32 v32, v26, v27
	v_cvt_pk_f16_f32 v33, v28, v29
	v_add_u32_e32 v186, s45, v185
	global_store_dwordx4 v186, v[30:33], s[100:101]
	v_pk_mul_f32 v[14:15], v[14:15], v[142:143] op_sel:[0,1] op_sel_hi:[1,1]
	v_pk_mul_f32 v[16:17], v[16:17], v[142:143] op_sel:[0,1] op_sel_hi:[1,1]
	v_pk_mul_f32 v[10:11], v[10:11], v[142:143] op_sel:[0,1] op_sel_hi:[1,1]
	v_pk_mul_f32 v[12:13], v[12:13], v[142:143] op_sel:[0,1] op_sel_hi:[1,1]
	v_cvt_pk_f16_f32 v14, v14, v15
	v_cvt_pk_f16_f32 v15, v16, v17
	v_cvt_pk_f16_f32 v16, v10, v11
	v_cvt_pk_f16_f32 v17, v12, v13
	v_add_u32_e32 v187, s45, v186
	global_store_dwordx4 v187, v[14:17], s[100:101]
	v_pk_mul_f32 v[54:55], v[54:55], v[146:147] op_sel_hi:[1,0]
	v_pk_mul_f32 v[56:57], v[56:57], v[146:147] op_sel_hi:[1,0]
	v_pk_mul_f32 v[50:51], v[50:51], v[146:147] op_sel_hi:[1,0]
	v_pk_mul_f32 v[52:53], v[52:53], v[146:147] op_sel_hi:[1,0]
	v_cvt_pk_f16_f32 v54, v54, v55
	v_cvt_pk_f16_f32 v55, v56, v57
	v_cvt_pk_f16_f32 v56, v50, v51
	v_cvt_pk_f16_f32 v57, v52, v53
	v_add_u32_e32 v184, s27, v183
	global_store_dwordx4 v184, v[54:57], s[100:101]
	v_pk_mul_f32 v[38:39], v[38:39], v[146:147] op_sel:[0,1] op_sel_hi:[1,1]
	v_pk_mul_f32 v[40:41], v[40:41], v[146:147] op_sel:[0,1] op_sel_hi:[1,1]
	v_pk_mul_f32 v[34:35], v[34:35], v[146:147] op_sel:[0,1] op_sel_hi:[1,1]
	v_pk_mul_f32 v[36:37], v[36:37], v[146:147] op_sel:[0,1] op_sel_hi:[1,1]
	v_cvt_pk_f16_f32 v38, v38, v39
	v_cvt_pk_f16_f32 v39, v40, v41
	v_cvt_pk_f16_f32 v40, v34, v35
	v_cvt_pk_f16_f32 v41, v36, v37
	v_add_u32_e32 v185, s45, v184
	global_store_dwordx4 v185, v[38:41], s[100:101]
	v_pk_mul_f32 v[22:23], v[22:23], v[142:143] op_sel_hi:[1,0]
	v_pk_mul_f32 v[24:25], v[24:25], v[142:143] op_sel_hi:[1,0]
	v_pk_mul_f32 v[18:19], v[18:19], v[142:143] op_sel_hi:[1,0]
	v_pk_mul_f32 v[20:21], v[20:21], v[142:143] op_sel_hi:[1,0]
	v_cvt_pk_f16_f32 v22, v22, v23
	v_cvt_pk_f16_f32 v23, v24, v25
	v_cvt_pk_f16_f32 v24, v18, v19
	v_cvt_pk_f16_f32 v25, v20, v21
	v_add_u32_e32 v186, s45, v185
	global_store_dwordx4 v186, v[22:25], s[100:101]
	v_pk_mul_f32 v[6:7], v[6:7], v[142:143] op_sel:[0,1] op_sel_hi:[1,1]
	v_pk_mul_f32 v[8:9], v[8:9], v[142:143] op_sel:[0,1] op_sel_hi:[1,1]
	v_pk_mul_f32 v[2:3], v[2:3], v[142:143] op_sel:[0,1] op_sel_hi:[1,1]
	v_pk_mul_f32 v[4:5], v[4:5], v[142:143] op_sel:[0,1] op_sel_hi:[1,1]
	v_cvt_pk_f16_f32 v6, v6, v7
	v_cvt_pk_f16_f32 v7, v8, v9
	v_cvt_pk_f16_f32 v8, v2, v3
	v_cvt_pk_f16_f32 v9, v4, v5
	v_add_u32_e32 v187, s45, v186
	global_store_dwordx4 v187, v[6:9], s[100:101]
	s_mov_b32 s30, 0x8000
	s_mov_b32 s31, s65
	v_readlane_b32 s76, v253, 5
	v_readlane_b32 s77, v253, 6
	v_readlane_b32 s78, v253, 7
	v_readlane_b32 s79, v253, 8
	s_movk_i32 s80, 0x4000
	s_movk_i32 s81, 0x1000
	v_readlane_b32 s84, v255, 30
	s_mov_b32 s85, 0x11000
	s_andn2_b64 vcc, exec, s[38:39]
	s_mov_b64 s[24:25], -1
	s_mov_b32 s56, 0x21000
	s_cbranch_vccnz .LBB0_149
	v_readlane_b32 s24, v255, 49
	v_readlane_b32 s25, v255, 50
	s_andn2_b64 vcc, exec, s[24:25]
	s_cbranch_vccnz .LBB0_148
	s_barrier
	s_branch .LBB0_148

; #define LAS __attribute__((address_space(3)))
; __global__ void __launch_bounds__(NTHR, 2) fwd_kernel(Args args) {
;     extern __shared__ __attribute__((aligned(16))) unsigned char lds_raw[];
;     cg::grid_group grid = cg::this_grid();
;     Frame F; F.lds = (LAS unsigned char*)lds_raw; F.tid = threadIdx.x; F.lane = F.tid & 63; F.wave = __builtin_amdgcn_readfirstlane(F.tid >> 6); F.G = gridDim.x;
	.amdhsa_kernel _Z10fwd_kernel4Args
		.amdhsa_group_segment_fixed_size 0
		.amdhsa_private_segment_fixed_size 0
		.amdhsa_kernarg_size 360
		.amdhsa_user_sgpr_count 2
		.amdhsa_user_sgpr_dispatch_ptr 0
		.amdhsa_user_sgpr_queue_ptr 0
		.amdhsa_user_sgpr_kernarg_segment_ptr 1
		.amdhsa_user_sgpr_dispatch_id 0
		.amdhsa_user_sgpr_kernarg_preload_length 0
		.amdhsa_user_sgpr_kernarg_preload_offset 0
		.amdhsa_user_sgpr_private_segment_size 0
		.amdhsa_uses_dynamic_stack 0
		.amdhsa_enable_private_segment 0
		.amdhsa_system_sgpr_workgroup_id_x 1
		.amdhsa_system_sgpr_workgroup_id_y 0
		.amdhsa_system_sgpr_workgroup_id_z 0
		.amdhsa_system_sgpr_workgroup_info 0
		.amdhsa_system_vgpr_workitem_id 2
		.amdhsa_next_free_vgpr 256
		.amdhsa_next_free_sgpr 102
		.amdhsa_accum_offset 256
		.amdhsa_reserve_vcc 1
		.amdhsa_float_round_mode_32 0
		.amdhsa_float_round_mode_16_64 0
		.amdhsa_float_denorm_mode_32 3
		.amdhsa_float_denorm_mode_16_64 3
		.amdhsa_dx10_clamp 1
		.amdhsa_ieee_mode 1
		.amdhsa_fp16_overflow 0
		.amdhsa_tg_split 0
		.amdhsa_exception_fp_ieee_invalid_op 0
		.amdhsa_exception_fp_denorm_src 0
		.amdhsa_exception_fp_ieee_div_zero 0
		.amdhsa_exception_fp_ieee_overflow 0
		.amdhsa_exception_fp_ieee_underflow 0
		.amdhsa_exception_fp_ieee_inexact 0
		.amdhsa_exception_int_div_zero 0
	.end_amdhsa_kernel

; #define LAS __attribute__((address_space(3)))
; __global__ void __launch_bounds__(NTHR, 2) fwd_kernel(Args args) {
;     extern __shared__ __attribute__((aligned(16))) unsigned char lds_raw[];
;     cg::grid_group grid = cg::this_grid();
;     Frame F; F.lds = (LAS unsigned char*)lds_raw; F.tid = threadIdx.x; F.lane = F.tid & 63; F.wave = __builtin_amdgcn_readfirstlane(F.tid >> 6); F.G = gridDim.x;
amdhsa.kernels:
  - .agpr_count:     0
    .args:
      - .offset:         0
        .size:           104
        .value_kind:     by_value
      - .offset:         104
        .size:           4
        .value_kind:     hidden_block_count_x
      - .offset:         108
        .size:           4
        .value_kind:     hidden_block_count_y
      - .offset:         112
        .size:           4
        .value_kind:     hidden_block_count_z
      - .offset:         116
        .size:           2
        .value_kind:     hidden_group_size_x
      - .offset:         118
        .size:           2
        .value_kind:     hidden_group_size_y
      - .offset:         120
        .size:           2
        .value_kind:     hidden_group_size_z
      - .offset:         122
        .size:           2
        .value_kind:     hidden_remainder_x
      - .offset:         124
        .size:           2
        .value_kind:     hidden_remainder_y
      - .offset:         126
        .size:           2
        .value_kind:     hidden_remainder_z
      - .offset:         144
        .size:           8
        .value_kind:     hidden_global_offset_x
      - .offset:         152
        .size:           8
        .value_kind:     hidden_global_offset_y
      - .offset:         160
        .size:           8
        .value_kind:     hidden_global_offset_z
      - .offset:         168
        .size:           2
        .value_kind:     hidden_grid_dims
      - .offset:         192
        .size:           8
        .value_kind:     hidden_multigrid_sync_arg
      - .offset:         224
        .size:           4
        .value_kind:     hidden_dynamic_lds_size
    .group_segment_fixed_size: 0
    .kernarg_segment_align: 8
    .kernarg_segment_size: 360
    .language:       OpenCL C
    .language_version:
      - 2
      - 0
    .max_flat_workgroup_size: 512
    .name:           _Z10fwd_kernel4Args
    .private_segment_fixed_size: 0
    .sgpr_count:     108
    .sgpr_spill_count: 197
    .symbol:         _Z10fwd_kernel4Args.kd
    .uniform_work_group_size: 1
    .uses_dynamic_stack: false
    .vgpr_count:     256
    .vgpr_spill_count: 0
    .wavefront_size: 64
